# scan blocks: one per CU (first claimer) with s_setprio 3 during scan jobs; partner block does GEMM tiles
# speedup vs baseline: 1.0764x; 1.0327x over previous
.LBB0_152:
	v_cmp_eq_u32_e64 s[10:11], 3, v0

.LBB0_156:
	s_or_b64 exec, exec, s[14:15]
	s_waitcnt vmcnt(0)
	v_readfirstlane_b32 s1, v1
	s_lshl_b64 s[8:9], s[8:9], 2
	v_readlane_b32 s14, v254, 11
	v_add_u32_e32 v0, s1, v0
	s_movk_i32 s1, 0x7fff
	v_cmp_gt_i32_e32 vcc, s1, v0
	v_readlane_b32 s15, v254, 12
	s_add_u32 s8, s14, s8
	v_cndmask_b32_e64 v0, 1, 2, vcc
	s_addc_u32 s9, s15, s9
	v_mov_b32_e32 v1, 0x2d569000
	global_store_dword v1, v0, s[8:9] offset:320 sc1
	s_andn2_b64 s[8:9], s[10:11], exec
	s_and_b64 s[10:11], vcc, exec
	s_or_b64 s[10:11], s[8:9], s[10:11]

.LBB0_199:
	s_or_b64 exec, exec, s[0:1]
	s_setprio 3
	v_add_u32_e32 v38, v0, v90
	v_ashrrev_i32_e32 v39, 31, v38
	v_lshlrev_b64 v[0:1], 10, v[38:39]
	v_lshl_add_u64 v[0:1], v[32:33], 0, v[0:1]
	v_lshl_add_u64 v[0:1], v[0:1], 0, v[64:65]
	v_lshlrev_b64 v[2:3], 1, v[0:1]
	v_lshl_add_u64 v[4:5], s[8:9], 0, v[2:3]
	v_lshl_add_u64 v[6:7], s[10:11], 0, v[2:3]
	v_lshl_add_u64 v[14:15], s[12:13], 0, v[2:3]
	v_lshl_add_u64 v[16:17], s[14:15], 0, v[2:3]
	global_load_dwordx2 v[40:41], v[4:5], off
	global_load_dwordx2 v[42:43], v[6:7], off
	global_load_dwordx2 v[44:45], v[14:15], off
	global_load_dwordx2 v[46:47], v[16:17], off
	v_add_u32_e32 v4, 16, v38
	v_ashrrev_i32_e32 v5, 31, v4
	v_lshlrev_b64 v[4:5], 10, v[4:5]
	v_lshl_add_u64 v[4:5], v[32:33], 0, v[4:5]
	v_lshl_add_u64 v[4:5], v[4:5], 0, v[64:65]
	v_lshlrev_b64 v[14:15], 1, v[4:5]
	v_lshl_add_u64 v[2:3], s[34:35], 0, v[2:3]
	v_lshl_add_u64 v[0:1], v[0:1], 2, s[36:37]
	v_lshl_add_u64 v[6:7], v[4:5], 2, s[36:37]
	v_lshl_add_u64 v[16:17], s[34:35], 0, v[14:15]
	global_load_dwordx2 v[48:49], v[2:3], off
	s_nop 0
	global_load_dwordx4 v[0:3], v[0:1], off
	s_nop 0
	global_load_dwordx4 v[4:7], v[6:7], off
	s_nop 0
	global_load_dwordx2 v[54:55], v[16:17], off
	v_lshl_add_u64 v[16:17], s[14:15], 0, v[14:15]
	v_lshl_add_u64 v[18:19], s[12:13], 0, v[14:15]
	v_lshl_add_u64 v[20:21], s[10:11], 0, v[14:15]
	v_lshl_add_u64 v[14:15], s[8:9], 0, v[14:15]
	global_load_dwordx2 v[62:63], v[16:17], off
	global_load_dwordx2 v[60:61], v[18:19], off
	global_load_dwordx2 v[58:59], v[20:21], off
	global_load_dwordx2 v[56:57], v[14:15], off
	v_readlane_b32 s0, v254, 27
	v_readlane_b32 s1, v254, 28
	v_lshlrev_b32_e32 v96, 1, v12
	v_mov_b32_e32 v67, v97
	v_lshl_add_u64 v[14:15], v[32:33], 1, s[0:1]
	v_lshl_add_u64 v[12:13], v[14:15], 0, v[96:97]
	v_readlane_b32 s0, v253, 21
	v_lshl_add_u32 v39, v36, 2, 0
	v_lshl_add_u64 v[50:51], v[12:13], 0, v[66:67]
	v_or_b32_e32 v52, v64, v32
	v_mov_b32_e32 v35, v33
	v_lshl_add_u32 v67, v36, 2, s0
	s_mov_b64 s[60:61], 0
	v_and_b32_e32 v177, 15, v176
	v_sub_u32_e32 v178, v38, v90
	v_add_u32_e32 v178, v178, v177
	v_lshlrev_b32_e32 v182, 1, v90
	v_mov_b32_e32 v183, v97
	v_lshl_add_u64 v[180:181], v[12:13], 0, v[182:183]
	v_readfirstlane_b32 s89, v75
	s_mov_b32 s88, 0
	s_waitcnt vmcnt(0)
	v_and_b32_e32 v77, 0xffff0000, v40
	v_lshlrev_b32_e32 v76, 16, v40
	v_and_b32_e32 v79, 0xffff0000, v41
	v_lshlrev_b32_e32 v78, 16, v41
	ds_write_b128 v103, v[76:79]
	v_and_b32_e32 v77, 0xffff0000, v42
	v_lshlrev_b32_e32 v76, 16, v42
	v_and_b32_e32 v79, 0xffff0000, v43
	v_lshlrev_b32_e32 v78, 16, v43
	ds_write_b128 v103, v[76:79] offset:8192
	v_and_b32_e32 v77, 0xffff0000, v44
	v_lshlrev_b32_e32 v76, 16, v44
	v_and_b32_e32 v79, 0xffff0000, v45
	v_lshlrev_b32_e32 v78, 16, v45
	ds_write_b128 v103, v[76:79] offset:12288
	v_and_b32_e32 v77, 0xffff0000, v46
	v_lshlrev_b32_e32 v76, 16, v46
	v_and_b32_e32 v79, 0xffff0000, v47
	v_lshlrev_b32_e32 v78, 16, v47
	ds_write_b128 v103, v[76:79] offset:16384
	v_and_b32_e32 v77, 0xffff0000, v48
	v_lshlrev_b32_e32 v76, 16, v48
	v_and_b32_e32 v79, 0xffff0000, v49
	v_lshlrev_b32_e32 v78, 16, v49
	ds_write_b128 v103, v[76:79] offset:20480
	ds_write_b128 v103, v[0:3] offset:4096
	s_add_i32 s7, s89, -1
	s_min_u32 s6, s7, 2
	v_lshl_add_u32 v122, s6, 4, v38
	v_ashrrev_i32_e32 v123, 31, v122
	v_lshlrev_b64 v[122:123], 10, v[122:123]
	v_or_b32_e32 v123, v123, v35
	v_or_b32_e32 v122, v122, v52
	v_lshlrev_b64 v[124:125], 1, v[122:123]
	v_lshl_add_u64 v[126:127], s[8:9], 0, v[124:125]
	global_load_dwordx2 v[40:41], v[126:127], off
	v_lshl_add_u64 v[128:129], s[10:11], 0, v[124:125]
	global_load_dwordx2 v[42:43], v[128:129], off
	v_lshl_add_u64 v[130:131], s[12:13], 0, v[124:125]
	global_load_dwordx2 v[44:45], v[130:131], off
	v_lshl_add_u64 v[132:133], s[14:15], 0, v[124:125]
	global_load_dwordx2 v[46:47], v[132:133], off
	v_lshl_add_u64 v[124:125], s[34:35], 0, v[124:125]
	global_load_dwordx2 v[48:49], v[124:125], off
	v_lshl_add_u64 v[122:123], v[122:123], 2, s[36:37]
	global_load_dwordx4 v[0:3], v[122:123], off
	s_waitcnt lgkmcnt(0)
	s_barrier

.LBB0_211:
	s_or_b64 exec, exec, s[60:61]
	s_setprio 0
	s_waitcnt vmcnt(1)
	v_mov_b32_e32 v2, s2
	v_mov_b32_e32 v3, s66
	v_cmp_gt_i32_e32 vcc, 4, v53
	v_readlane_b32 s0, v254, 15
	v_readlane_b32 s1, v254, 16
	v_cndmask_b32_e32 v2, v2, v3, vcc
	v_add_u32_e32 v2, v2, v53
	v_cndmask_b32_e32 v96, v205, v250, vcc
	v_ashrrev_i32_e32 v3, 31, v2
	v_lshl_add_u64 v[0:1], v[32:33], 0, v[36:37]
	v_lshl_add_u64 v[4:5], s[0:1], 0, v[96:97]
	v_lshlrev_b64 v[2:3], 18, v[2:3]
	v_lshlrev_b64 v[0:1], 8, v[0:1]
	v_lshl_add_u64 v[2:3], v[4:5], 0, v[2:3]
	v_lshl_add_u64 v[0:1], v[2:3], 0, v[0:1]
	v_mov_b32_e32 v35, v97
	v_lshl_add_u64 v[0:1], v[0:1], 0, v[34:35]
	s_xor_b64 s[0:1], exec, -1
	global_store_dwordx4 v[0:1], v[8:11], off
	s_barrier
